# SUBLN-LDS: attention epilogue reads the sub-layer-norm weights from an LDS copy (made once per phase) instead of 16 global loads per unit issued behind each output store, so no wait covers a just-issu
# speedup vs baseline: 1.0059x; 1.0002x over previous
.LBB0_969:
	s_cmp_lt_i32 s62, 8
	s_cselect_b64 s[0:1], -1, 0
	s_and_b64 s[12:13], s[0:1], s[4:5]
	s_andn2_b64 vcc, exec, s[12:13]
	s_cbranch_vccnz .LBB0_993
	s_load_dwordx4 s[4:7], s[60:61], 0xc0
	v_and_b32_e32 v2, 63, v0
	v_lshlrev_b32_e32 v1, 2, v2
	s_cmpk_gt_i32 s58, 0x4ff
	s_waitcnt lgkmcnt(0)
	global_load_dword v3, v1, s[6:7]
	global_load_dword v4, v1, s[6:7] offset:256
	global_load_dword v5, v1, s[6:7] offset:512
	global_load_dword v6, v1, s[6:7] offset:768
	global_load_dword v7, v1, s[4:5]
	v_mbcnt_lo_u32_b32 v1, -1, 0
	v_mbcnt_hi_u32_b32 v1, -1, v1
	v_and_b32_e32 v8, 64, v1
	v_xor_b32_e32 v9, 1, v1
	v_add_u32_e32 v8, 64, v8
	v_xor_b32_e32 v10, 2, v1
	v_cmp_lt_i32_e32 vcc, v9, v8
	v_xor_b32_e32 v11, 4, v1
	v_xor_b32_e32 v12, 8, v1
	v_cndmask_b32_e32 v9, v1, v9, vcc
	v_cmp_lt_i32_e32 vcc, v10, v8
	v_xor_b32_e32 v13, 16, v1
	v_xor_b32_e32 v14, 32, v1
	v_cndmask_b32_e32 v10, v1, v10, vcc
	v_cmp_lt_i32_e32 vcc, v11, v8
	s_mov_b32 s7, 0
	s_waitcnt vmcnt(0)
	v_and_b32_e32 v15, 0x7fffffff, v7
	v_cndmask_b32_e32 v11, v1, v11, vcc
	v_cmp_lt_i32_e32 vcc, v12, v8
	v_max_f32_e64 v7, |v7|, |v7|
	s_nop 0
	v_cndmask_b32_e32 v12, v1, v12, vcc
	v_cmp_lt_i32_e32 vcc, v13, v8
	s_nop 1
	v_cndmask_b32_e32 v13, v1, v13, vcc
	v_cmp_lt_i32_e32 vcc, v14, v8
	v_lshlrev_b32_e32 v8, 2, v9
	v_lshlrev_b32_e32 v9, 2, v10
	v_cndmask_b32_e32 v1, v1, v14, vcc
	v_lshlrev_b32_e32 v10, 2, v11
	v_lshlrev_b32_e32 v11, 2, v12
	v_lshlrev_b32_e32 v12, 2, v13
	v_mul_f32_e32 v13, v3, v4
	v_mul_f32_e32 v14, v5, v6
	ds_bpermute_b32 v13, v8, v13
	ds_bpermute_b32 v14, v8, v14
	ds_bpermute_b32 v8, v8, v15
	v_lshlrev_b32_e32 v1, 2, v1
	s_waitcnt lgkmcnt(2)
	v_fmac_f32_e32 v13, v3, v4
	s_waitcnt lgkmcnt(1)
	v_fmac_f32_e32 v14, v5, v6
	s_waitcnt lgkmcnt(0)
	v_max_f32_e32 v5, v8, v8
	v_max_f32_e32 v5, v7, v5
	ds_bpermute_b32 v6, v9, v5
	ds_bpermute_b32 v3, v9, v13
	ds_bpermute_b32 v4, v9, v14
	s_waitcnt lgkmcnt(2)
	v_max_f32_e32 v6, v6, v6
	v_max_f32_e32 v5, v5, v6
	ds_bpermute_b32 v6, v10, v5
	s_waitcnt lgkmcnt(2)
	v_add_f32_e32 v3, v13, v3
	s_waitcnt lgkmcnt(1)
	v_add_f32_e32 v4, v14, v4
	ds_bpermute_b32 v7, v10, v3
	ds_bpermute_b32 v8, v10, v4
	s_waitcnt lgkmcnt(2)
	v_max_f32_e32 v6, v6, v6
	v_max_f32_e32 v5, v5, v6
	ds_bpermute_b32 v6, v11, v5
	s_waitcnt lgkmcnt(2)
	v_add_f32_e32 v3, v3, v7
	s_waitcnt lgkmcnt(1)
	v_add_f32_e32 v4, v4, v8
	ds_bpermute_b32 v7, v11, v3
	ds_bpermute_b32 v8, v11, v4
	s_waitcnt lgkmcnt(2)
	v_max_f32_e32 v6, v6, v6
	v_max_f32_e32 v9, v5, v6
	ds_bpermute_b32 v10, v12, v9
	s_waitcnt lgkmcnt(2)
	v_add_f32_e32 v3, v3, v7
	s_waitcnt lgkmcnt(1)
	v_add_f32_e32 v4, v4, v8
	ds_bpermute_b32 v7, v12, v3
	ds_bpermute_b32 v8, v12, v4
	s_waitcnt lgkmcnt(1)
	v_add_f32_e32 v5, v3, v7
	v_max_f32_e32 v3, v10, v10
	s_waitcnt lgkmcnt(0)
	v_add_f32_e32 v7, v4, v8
	v_max_f32_e32 v3, v9, v3
	ds_bpermute_b32 v6, v1, v5
	ds_bpermute_b32 v8, v1, v7
	ds_bpermute_b32 v4, v1, v3
	s_cbranch_scc1 .LBB0_993
	s_load_dwordx4 s[8:11], s[60:61], 0xf8
	s_load_dwordx2 s[4:5], s[60:61], 0xd0
	s_waitcnt lgkmcnt(0)
	v_add_f32_e32 v5, v5, v6
	v_add_f32_e32 v6, v7, v8
	v_mul_f32_e32 v5, 0x3fb8aa3b, v5
	v_mul_f32_e32 v6, 0x3fb8aa3b, v6
	v_exp_f32_e32 v5, v5
	v_exp_f32_e32 v6, v6
	s_add_u32 s14, s10, 0x9500000
	s_addc_u32 s15, s11, 0
	s_add_u32 s0, s10, 0xbd00000
	v_sub_f32_e32 v5, v5, v6
	v_max_f32_e32 v4, v4, v4
	v_max_f32_e32 v3, v3, v3
	s_addc_u32 s1, s11, 0
	v_add_f32_e32 v148, 0x3e4ccccd, v5
	v_max_f32_e32 v3, v3, v4
	v_lshlrev_b32_e32 v5, 3, v0
	s_add_u32 s2, s10, 0xc500000
	v_mul_f32_e32 v3, 0x41000000, v3
	v_and_b32_e32 v6, 24, v5
	v_lshlrev_b32_e32 v5, 1, v0
	v_lshlrev_b32_e32 v7, 4, v0
	s_addc_u32 s3, s11, 0
	v_mul_f32_e32 v149, 0x3f8147ae, v3
	v_lshrrev_b32_e32 v3, 5, v2
	v_and_b32_e32 v5, 32, v5
	v_and_b32_e32 v7, 0xc0, v7
	s_add_u32 s30, s8, 0x800000
	v_lshl_or_b32 v7, v3, 8, v7
	v_add_u32_e32 v5, 0, v5
	s_addc_u32 s31, s9, 0
	v_and_b32_e32 v151, 31, v0
	v_lshlrev_b32_e32 v8, 3, v3
	v_add3_u32 v153, v5, v7, v6
	v_lshlrev_b32_e32 v5, 10, v3
	v_lshlrev_b32_e32 v130, 4, v3
	v_mov_b32_e32 v3, 0x20000
	s_add_u32 s33, s10, 0x32000
	v_lshl_add_u32 v150, v2, 2, 0
	v_lshlrev_b32_e32 v4, 10, v2
	v_mov_b32_e32 v131, 0
	v_lshrrev_b32_e32 v152, 2, v2
	v_lshlrev_b32_e32 v7, 4, v151
	v_lshl_or_b32 v134, v2, 11, v3
	v_and_b32_e32 v2, 3, v0
	s_addc_u32 s34, s11, 0
	v_add3_u32 v154, 0, v5, v7
	v_lshl_add_u64 v[132:133], s[4:5], 0, v[130:131]
	v_add_u32_e32 v193, 0x18000, v130
	v_cmp_gt_u32_e32 vcc, 0x80, v0
	s_and_saveexec_b64 s[76:77], vcc
	s_cbranch_execz .Lsubl_skip
	v_lshlrev_b32_e32 v249, 2, v0
	global_load_dword v250, v249, s[4:5]
	v_add_u32_e32 v249, 0x18000, v249
	s_waitcnt vmcnt(0)
	ds_write_b32 v249, v250
.Lsubl_skip:
	s_or_b64 exec, exec, s[76:77]
	v_mov_b32_e32 v135, v131
	v_lshl_or_b32 v136, v2, 4, v3
	v_mov_b32_e32 v137, v131
	v_lshlrev_b32_e32 v155, 10, v152
	v_lshlrev_b32_e32 v130, 1, v4
	v_lshlrev_b32_e32 v138, 1, v6
	s_mov_b64 s[16:17], 0x80
	v_lshlrev_b32_e32 v140, 1, v8
	s_mov_b32 s35, 0xffff0000
	s_mov_b32 s36, 0xf800000
	v_mov_b32_e32 v156, 0x260
	s_mov_b64 s[18:19], 0x20000
	s_mov_b64 s[20:21], 0x4500800
	s_mov_b32 s37, 0x4500000
	v_mov_b32_e32 v157, 0x358637bd
	s_mov_b32 s38, 0x800000
	s_movk_i32 s39, 0x7fff
	v_mov_b32_e32 v158, 1
	s_mov_b32 s40, s58
	s_branch .LBB0_973

.LBB0_991:
	s_waitcnt vmcnt(0) lgkmcnt(0)
	s_barrier
	s_andn2_b64 vcc, exec, s[4:5]
	s_cbranch_vccnz .LBB0_972
	v_lshlrev_b64 v[66:67], 12, v[142:143]
	v_lshl_add_u64 v[66:67], s[10:11], 0, v[66:67]
	s_lshl_b32 s6, s26, 1
	v_lshl_add_u64 v[66:67], v[66:67], 0, s[6:7]
	v_mov_b32_e32 v141, v131
	v_lshl_add_u64 v[78:79], v[66:67], 0, v[140:141]
	v_add_co_u32_e32 v84, vcc, s37, v78
	s_nop 1
	v_mov_b32_e32 v110, v14
	v_addc_co_u32_e32 v85, vcc, 0, v79, vcc
	global_load_dwordx4 v[66:69], v[84:85], off offset:2048
	ds_read2st64_b32 v[80:81], v70 offset1:1
	ds_read2st64_b32 v[124:125], v70 offset0:2 offset1:3
	ds_read2st64_b32 v[142:143], v70 offset0:4 offset1:5
	ds_read2st64_b32 v[106:107], v70 offset0:6 offset1:7
	ds_read2st64_b32 v[104:105], v70 offset0:8 offset1:9
	ds_read2st64_b32 v[102:103], v70 offset0:10 offset1:11
	ds_read2st64_b32 v[100:101], v70 offset0:12 offset1:13
	ds_read2st64_b32 v[98:99], v70 offset0:14 offset1:15
	ds_read2st64_b32 v[96:97], v70 offset0:16 offset1:17
	ds_read2st64_b32 v[94:95], v70 offset0:18 offset1:19
	ds_read2st64_b32 v[92:93], v70 offset0:20 offset1:21
	ds_read2st64_b32 v[90:91], v70 offset0:22 offset1:23
	ds_read2st64_b32 v[88:89], v70 offset0:24 offset1:25
	ds_read2st64_b32 v[86:87], v70 offset0:26 offset1:27
	ds_read2st64_b32 v[112:113], v70 offset0:28 offset1:29
	ds_read2st64_b32 v[116:117], v70 offset0:30 offset1:31
	ds_read_b128 v[74:77], v193
	ds_read_b128 v[70:73], v193 offset:32
	v_mov_b32_e32 v111, v16
	v_mov_b32_e32 v16, v15
	s_waitcnt lgkmcnt(3)
	v_cvt_f32_f16_e32 v15, v113
	v_cvt_f32_f16_e32 v14, v112
	v_cvt_f32_f16_sdwa v113, v113 dst_sel:DWORD dst_unused:UNUSED_PAD src0_sel:WORD_1
	v_cvt_f32_f16_sdwa v112, v112 dst_sel:DWORD dst_unused:UNUSED_PAD src0_sel:WORD_1
	s_waitcnt lgkmcnt(2)
	v_cvt_f32_f16_e32 v115, v117
	v_cvt_f32_f16_e32 v114, v116
	v_cvt_f32_f16_sdwa v117, v117 dst_sel:DWORD dst_unused:UNUSED_PAD src0_sel:WORD_1
	v_cvt_f32_f16_sdwa v116, v116 dst_sel:DWORD dst_unused:UNUSED_PAD src0_sel:WORD_1
	v_cvt_f32_f16_sdwa v123, v80 dst_sel:DWORD dst_unused:UNUSED_PAD src0_sel:WORD_1
	v_cvt_f32_f16_e32 v122, v80
	v_cvt_f32_f16_sdwa v127, v143 dst_sel:DWORD dst_unused:UNUSED_PAD src0_sel:WORD_1
	v_cvt_f32_f16_e32 v126, v143
	v_cvt_f32_f16_sdwa v143, v142 dst_sel:DWORD dst_unused:UNUSED_PAD src0_sel:WORD_1
	v_cvt_f32_f16_e32 v142, v142
	v_mov_b32_e32 v108, v10
	v_mov_b32_e32 v109, v12
	v_mov_b32_e32 v12, v11
	v_pk_fma_f32 v[144:145], v[108:109], v[82:83], v[14:15] op_sel_hi:[1,0,1] neg_lo:[0,0,1] neg_hi:[0,0,1]
	v_pk_fma_f32 v[14:15], v[12:13], v[82:83], v[112:113] op_sel_hi:[1,0,1] neg_lo:[0,0,1] neg_hi:[0,0,1]
	v_pk_fma_f32 v[12:13], v[16:17], v[82:83], v[116:117] op_sel_hi:[1,0,1] neg_lo:[0,0,1] neg_hi:[0,0,1]
	v_pk_mul_f32 v[16:17], v[14:15], v[14:15]
	v_pk_fma_f32 v[108:109], v[110:111], v[82:83], v[114:115] op_sel_hi:[1,0,1] neg_lo:[0,0,1] neg_hi:[0,0,1]
	v_pk_fma_f32 v[114:115], v[50:51], v[82:83], v[122:123] op_sel_hi:[1,0,1] neg_lo:[0,0,1] neg_hi:[0,0,1]
	v_pk_fma_f32 v[122:123], v[58:59], v[82:83], v[142:143] op_sel_hi:[1,0,1] neg_lo:[0,0,1] neg_hi:[0,0,1]
	v_pk_fma_f32 v[142:143], v[144:145], v[144:145], v[16:17]
	v_cvt_f32_f16_sdwa v17, v106 dst_sel:DWORD dst_unused:UNUSED_PAD src0_sel:WORD_1
	v_cvt_f32_f16_e32 v16, v106
	v_cvt_f32_f16_sdwa v119, v81 dst_sel:DWORD dst_unused:UNUSED_PAD src0_sel:WORD_1
	v_cvt_f32_f16_e32 v118, v81
	v_pk_mul_f32 v[50:51], v[12:13], v[12:13]
	v_pk_fma_f32 v[160:161], v[62:63], v[82:83], v[16:17] op_sel_hi:[1,0,1] neg_lo:[0,0,1] neg_hi:[0,0,1]
	v_cvt_f32_f16_sdwa v17, v103 dst_sel:DWORD dst_unused:UNUSED_PAD src0_sel:WORD_1
	v_cvt_f32_f16_e32 v16, v103
	v_pk_fma_f32 v[146:147], v[108:109], v[108:109], v[50:51]
	v_cvt_f32_f16_sdwa v51, v105 dst_sel:DWORD dst_unused:UNUSED_PAD src0_sel:WORD_1
	v_cvt_f32_f16_e32 v50, v105
	v_cvt_f32_f16_sdwa v121, v125 dst_sel:DWORD dst_unused:UNUSED_PAD src0_sel:WORD_1
	v_cvt_f32_f16_e32 v120, v125
	v_pk_fma_f32 v[110:111], v[52:53], v[82:83], v[118:119] op_sel_hi:[1,0,1] neg_lo:[0,0,1] neg_hi:[0,0,1]
	v_pk_fma_f32 v[52:53], v[40:41], v[82:83], v[16:17] op_sel_hi:[1,0,1] neg_lo:[0,0,1] neg_hi:[0,0,1]
	v_cvt_f32_f16_sdwa v17, v102 dst_sel:DWORD dst_unused:UNUSED_PAD src0_sel:WORD_1
	v_cvt_f32_f16_e32 v16, v102
	v_cvt_f32_f16_sdwa v125, v124 dst_sel:DWORD dst_unused:UNUSED_PAD src0_sel:WORD_1
	v_cvt_f32_f16_e32 v124, v124
	v_pk_fma_f32 v[50:51], v[36:37], v[82:83], v[50:51] op_sel_hi:[1,0,1] neg_lo:[0,0,1] neg_hi:[0,0,1]
	v_cvt_f32_f16_sdwa v37, v104 dst_sel:DWORD dst_unused:UNUSED_PAD src0_sel:WORD_1
	v_cvt_f32_f16_e32 v36, v104
	v_cvt_f32_f16_sdwa v129, v107 dst_sel:DWORD dst_unused:UNUSED_PAD src0_sel:WORD_1
	v_cvt_f32_f16_e32 v128, v107
	v_pk_fma_f32 v[112:113], v[56:57], v[82:83], v[120:121] op_sel_hi:[1,0,1] neg_lo:[0,0,1] neg_hi:[0,0,1]
	v_pk_fma_f32 v[56:57], v[38:39], v[82:83], v[16:17] op_sel_hi:[1,0,1] neg_lo:[0,0,1] neg_hi:[0,0,1]
	v_cvt_f32_f16_sdwa v17, v99 dst_sel:DWORD dst_unused:UNUSED_PAD src0_sel:WORD_1
	v_cvt_f32_f16_e32 v16, v99
	v_pk_fma_f32 v[116:117], v[54:55], v[82:83], v[124:125] op_sel_hi:[1,0,1] neg_lo:[0,0,1] neg_hi:[0,0,1]
	v_pk_fma_f32 v[54:55], v[34:35], v[82:83], v[36:37] op_sel_hi:[1,0,1] neg_lo:[0,0,1] neg_hi:[0,0,1]
	v_cvt_f32_f16_sdwa v35, v101 dst_sel:DWORD dst_unused:UNUSED_PAD src0_sel:WORD_1
	v_cvt_f32_f16_e32 v34, v101
	v_pk_fma_f32 v[120:121], v[64:65], v[82:83], v[128:129] op_sel_hi:[1,0,1] neg_lo:[0,0,1] neg_hi:[0,0,1]
	v_pk_mul_f32 v[58:59], v[110:111], v[110:111]
	v_pk_mul_f32 v[64:65], v[114:115], v[114:115]
	v_pk_mul_f32 v[124:125], v[116:117], v[116:117]
	v_pk_fma_f32 v[48:49], v[48:49], v[82:83], v[16:17] op_sel_hi:[1,0,1] neg_lo:[0,0,1] neg_hi:[0,0,1]
	v_cvt_f32_f16_sdwa v17, v98 dst_sel:DWORD dst_unused:UNUSED_PAD src0_sel:WORD_1
	v_cvt_f32_f16_e32 v16, v98
	v_add_f32_e32 v58, v58, v59
	v_add_f32_e32 v59, v64, v65
	v_pk_fma_f32 v[118:119], v[60:61], v[82:83], v[126:127] op_sel_hi:[1,0,1] neg_lo:[0,0,1] neg_hi:[0,0,1]
	v_pk_mul_f32 v[60:61], v[112:113], v[112:113]
	v_pk_fma_f32 v[44:45], v[44:45], v[82:83], v[34:35] op_sel_hi:[1,0,1] neg_lo:[0,0,1] neg_hi:[0,0,1]
	v_cvt_f32_f16_sdwa v35, v100 dst_sel:DWORD dst_unused:UNUSED_PAD src0_sel:WORD_1
	v_cvt_f32_f16_e32 v34, v100
	v_add_f32_e32 v58, v59, v58
	v_pk_mul_f32 v[106:107], v[122:123], v[122:123]
	v_add_f32_e32 v59, v60, v61
	s_waitcnt vmcnt(0)
	v_mov_b32_e32 v139, v68
	s_nop 1
	v_permlane32_swap_b32_e32 v66, v139
	v_mov_b32_e32 v141, v69
	v_lshlrev_b32_e32 v68, 16, v66
	v_and_b32_e32 v69, 0xffff0000, v66
	v_add_f32_e32 v66, v124, v125
	v_add_f32_e32 v58, v58, v66
	v_pk_mul_f32 v[126:127], v[118:119], v[118:119]
	v_add_f32_e32 v58, v58, v59
	v_add_f32_e32 v59, v106, v107
	v_pk_mul_f32 v[62:63], v[160:161], v[160:161]
	v_pk_fma_f32 v[46:47], v[46:47], v[82:83], v[16:17] op_sel_hi:[1,0,1] neg_lo:[0,0,1] neg_hi:[0,0,1]
	v_cvt_f32_f16_sdwa v17, v95 dst_sel:DWORD dst_unused:UNUSED_PAD src0_sel:WORD_1
	v_cvt_f32_f16_e32 v16, v95
	v_add_f32_e32 v58, v58, v59
	v_add_f32_e32 v59, v126, v127
	v_pk_mul_f32 v[128:129], v[120:121], v[120:121]
	v_pk_fma_f32 v[42:43], v[42:43], v[82:83], v[34:35] op_sel_hi:[1,0,1] neg_lo:[0,0,1] neg_hi:[0,0,1]
	v_cvt_f32_f16_sdwa v35, v97 dst_sel:DWORD dst_unused:UNUSED_PAD src0_sel:WORD_1
	v_cvt_f32_f16_e32 v34, v97
	v_add_f32_e32 v58, v58, v59
	v_add_f32_e32 v59, v62, v63
	v_pk_mul_f32 v[102:103], v[54:55], v[54:55]
	v_add_f32_e32 v58, v58, v59
	v_add_f32_e32 v59, v128, v129
	v_pk_mul_f32 v[104:105], v[50:51], v[50:51]
	v_add_f32_e32 v58, v58, v59
	v_add_f32_e32 v59, v102, v103
	v_pk_mul_f32 v[164:165], v[56:57], v[56:57]
	v_pk_fma_f32 v[36:37], v[24:25], v[82:83], v[16:17] op_sel_hi:[1,0,1] neg_lo:[0,0,1] neg_hi:[0,0,1]
	v_cvt_f32_f16_sdwa v17, v94 dst_sel:DWORD dst_unused:UNUSED_PAD src0_sel:WORD_1
	v_cvt_f32_f16_e32 v16, v94
	v_add_f32_e32 v58, v58, v59
	v_add_f32_e32 v59, v104, v105
	v_pk_mul_f32 v[162:163], v[52:53], v[52:53]
	v_pk_fma_f32 v[34:35], v[20:21], v[82:83], v[34:35] op_sel_hi:[1,0,1] neg_lo:[0,0,1] neg_hi:[0,0,1]
	v_cvt_f32_f16_sdwa v21, v96 dst_sel:DWORD dst_unused:UNUSED_PAD src0_sel:WORD_1
	v_cvt_f32_f16_e32 v20, v96
	v_add_f32_e32 v58, v58, v59
	v_add_f32_e32 v59, v164, v165
	v_pk_mul_f32 v[98:99], v[42:43], v[42:43]
	v_add_f32_e32 v58, v58, v59
	v_add_f32_e32 v59, v162, v163
	v_pk_mul_f32 v[100:101], v[44:45], v[44:45]
	v_add_f32_e32 v58, v58, v59
	v_add_f32_e32 v59, v98, v99
	v_pk_mul_f32 v[170:171], v[46:47], v[46:47]
	v_pk_fma_f32 v[40:41], v[22:23], v[82:83], v[16:17] op_sel_hi:[1,0,1] neg_lo:[0,0,1] neg_hi:[0,0,1]
	v_cvt_f32_f16_sdwa v17, v91 dst_sel:DWORD dst_unused:UNUSED_PAD src0_sel:WORD_1
	v_cvt_f32_f16_e32 v16, v91
	v_cvt_f32_f16_sdwa v23, v92 dst_sel:DWORD dst_unused:UNUSED_PAD src0_sel:WORD_1
	v_cvt_f32_f16_e32 v22, v92
	v_cvt_f32_f16_sdwa v91, v90 dst_sel:DWORD dst_unused:UNUSED_PAD src0_sel:WORD_1
	v_cvt_f32_f16_e32 v90, v90
	v_add_f32_e32 v58, v58, v59
	v_add_f32_e32 v59, v100, v101
	v_pk_mul_f32 v[168:169], v[48:49], v[48:49]
	v_pk_fma_f32 v[38:39], v[18:19], v[82:83], v[20:21] op_sel_hi:[1,0,1] neg_lo:[0,0,1] neg_hi:[0,0,1]
	v_add_f32_e32 v58, v58, v59
	v_add_f32_e32 v59, v170, v171
	v_cvt_f32_f16_sdwa v19, v93 dst_sel:DWORD dst_unused:UNUSED_PAD src0_sel:WORD_1
	v_cvt_f32_f16_e32 v18, v93
	v_pk_mul_f32 v[94:95], v[38:39], v[38:39]
	v_add_f32_e32 v58, v58, v59
	v_add_f32_e32 v59, v168, v169
	v_pk_mul_f32 v[96:97], v[34:35], v[34:35]
	v_add_f32_e32 v58, v58, v59
	v_add_f32_e32 v59, v94, v95
	v_pk_mul_f32 v[174:175], v[40:41], v[40:41]
	v_pk_fma_f32 v[20:21], v[32:33], v[82:83], v[16:17] op_sel_hi:[1,0,1] neg_lo:[0,0,1] neg_hi:[0,0,1]
	v_pk_fma_f32 v[24:25], v[26:27], v[82:83], v[22:23] op_sel_hi:[1,0,1] neg_lo:[0,0,1] neg_hi:[0,0,1]
	v_pk_fma_f32 v[22:23], v[30:31], v[82:83], v[90:91] op_sel_hi:[1,0,1] neg_lo:[0,0,1] neg_hi:[0,0,1]
	v_cvt_f32_f16_sdwa v33, v89 dst_sel:DWORD dst_unused:UNUSED_PAD src0_sel:WORD_1
	v_cvt_f32_f16_e32 v32, v89
	v_cvt_f32_f16_sdwa v91, v87 dst_sel:DWORD dst_unused:UNUSED_PAD src0_sel:WORD_1
	v_cvt_f32_f16_e32 v90, v87
	v_cvt_f32_f16_sdwa v89, v88 dst_sel:DWORD dst_unused:UNUSED_PAD src0_sel:WORD_1
	v_cvt_f32_f16_e32 v88, v88
	v_add_f32_e32 v58, v58, v59
	v_add_f32_e32 v59, v96, v97
	v_pk_mul_f32 v[172:173], v[36:37], v[36:37]
	v_add_f32_e32 v58, v58, v59
	v_add_f32_e32 v59, v174, v175
	v_pk_fma_f32 v[18:19], v[28:29], v[82:83], v[18:19] op_sel_hi:[1,0,1] neg_lo:[0,0,1] neg_hi:[0,0,1]
	v_pk_mul_f32 v[26:27], v[24:25], v[24:25]
	v_mov_b32_e32 v30, v23
	v_mov_b32_e32 v31, v21
	v_cvt_f32_f16_sdwa v87, v86 dst_sel:DWORD dst_unused:UNUSED_PAD src0_sel:WORD_1
	v_cvt_f32_f16_e32 v86, v86
	v_add_f32_e32 v58, v58, v59
	v_add_f32_e32 v59, v172, v173
	v_pk_mul_f32 v[28:29], v[18:19], v[18:19]
	v_mov_b32_e32 v16, v22
	v_mov_b32_e32 v17, v20
	v_pk_mul_f32 v[30:31], v[30:31], v[30:31]
	v_add_f32_e32 v58, v58, v59
	v_add_f32_e32 v26, v26, v27
	v_pk_fma_f32 v[30:31], v[16:17], v[16:17], v[30:31]
	v_pk_fma_f32 v[16:17], v[4:5], v[82:83], v[32:33] op_sel_hi:[1,0,1] neg_lo:[0,0,1] neg_hi:[0,0,1]
	v_pk_fma_f32 v[4:5], v[8:9], v[82:83], v[90:91] op_sel_hi:[1,0,1] neg_lo:[0,0,1] neg_hi:[0,0,1]
	v_pk_fma_f32 v[8:9], v[2:3], v[82:83], v[88:89] op_sel_hi:[1,0,1] neg_lo:[0,0,1] neg_hi:[0,0,1]
	v_add_f32_e32 v26, v58, v26
	v_add_f32_e32 v27, v28, v29
	v_mov_b32_e32 v32, v9
	v_mov_b32_e32 v33, v17
	v_add_f32_e32 v26, v26, v27
	v_mov_b32_e32 v2, v8
	v_mov_b32_e32 v3, v16
	v_pk_mul_f32 v[32:33], v[32:33], v[32:33]
	v_pk_fma_f32 v[6:7], v[6:7], v[82:83], v[86:87] op_sel_hi:[1,0,1] neg_lo:[0,0,1] neg_hi:[0,0,1]
	v_add_f32_e32 v26, v26, v30
	v_pk_fma_f32 v[2:3], v[2:3], v[2:3], v[32:33]
	v_mov_b32_e32 v82, v7
	v_mov_b32_e32 v83, v5
	v_add_f32_e32 v26, v26, v31
	v_mov_b32_e32 v32, v6
	v_mov_b32_e32 v33, v4
	v_pk_mul_f32 v[82:83], v[82:83], v[82:83]
	v_add_f32_e32 v2, v26, v2
	v_pk_fma_f32 v[32:33], v[32:33], v[32:33], v[82:83]
	v_add_f32_e32 v2, v2, v3
	v_add_f32_e32 v2, v2, v32
	v_add_f32_e32 v2, v2, v33
	v_add_f32_e32 v2, v2, v142
	v_add_f32_e32 v2, v2, v143
	v_add_f32_e32 v2, v2, v146
	v_add_f32_e32 v2, v2, v147
	ds_bpermute_b32 v3, v1, v2
	v_permlane32_swap_b32_e32 v67, v141
	v_lshlrev_b32_e32 v30, 16, v67
	v_and_b32_e32 v31, 0xffff0000, v67
	s_waitcnt lgkmcnt(0)
	v_add_f32_e32 v2, v2, v3
	v_fmamk_f32 v2, v2, 0x3c000000, v157
	v_mul_f32_e32 v3, 0x4b800000, v2
	v_cmp_gt_f32_e32 vcc, s38, v2
	v_lshlrev_b32_e32 v32, 16, v139
	v_and_b32_e32 v33, 0xffff0000, v139
	v_cndmask_b32_e32 v2, v2, v3, vcc
	v_rsq_f32_e32 v2, v2
	v_lshlrev_b32_e32 v58, 16, v141
	v_and_b32_e32 v59, 0xffff0000, v141
	v_lshl_add_u64 v[10:11], v[78:79], 0, s[20:21]
	v_mul_f32_e32 v3, 0x45800000, v2
	v_cndmask_b32_e32 v2, v2, v3, vcc
	v_mul_f32_e32 v2, 0x3f4ccccd, v2
	v_pk_mul_f32 v[62:63], v[110:111], v[2:3] op_sel_hi:[1,0]
	v_pk_mul_f32 v[60:61], v[114:115], v[2:3] op_sel_hi:[1,0]
	v_pk_mul_f32 v[62:63], v[76:77], v[62:63]
	v_pk_mul_f32 v[60:61], v[74:75], v[60:61]
	v_pk_mul_f32 v[62:63], v[62:63], v[30:31]
	v_pk_mul_f32 v[30:31], v[116:117], v[2:3] op_sel_hi:[1,0]
	v_pk_mul_f32 v[60:61], v[60:61], v[68:69]
	v_pk_mul_f32 v[30:31], v[70:71], v[30:31]
	global_load_dwordx4 v[78:81], v[10:11], off offset:224
	global_load_dwordx4 v[26:29], v[10:11], off offset:32
	v_pk_mul_f32 v[32:33], v[30:31], v[32:33]
	v_pk_mul_f32 v[30:31], v[112:113], v[2:3] op_sel_hi:[1,0]
	v_and_b32_sdwa v3, v61, v158 dst_sel:DWORD dst_unused:UNUSED_PAD src0_sel:WORD_1 src1_sel:DWORD
	v_pk_mul_f32 v[30:31], v[72:73], v[30:31]
	v_add3_u32 v3, v61, v3, s39
	v_pk_mul_f32 v[58:59], v[30:31], v[58:59]
	v_and_b32_sdwa v30, v60, v158 dst_sel:DWORD dst_unused:UNUSED_PAD src0_sel:WORD_1 src1_sel:DWORD
	v_add3_u32 v30, v60, v30, s39
	v_lshrrev_b32_e32 v30, 16, v30
	v_and_b32_sdwa v31, v32, v158 dst_sel:DWORD dst_unused:UNUSED_PAD src0_sel:WORD_1 src1_sel:DWORD
	v_and_or_b32 v30, v3, s35, v30
	v_and_b32_sdwa v3, v33, v158 dst_sel:DWORD dst_unused:UNUSED_PAD src0_sel:WORD_1 src1_sel:DWORD
	v_add3_u32 v31, v32, v31, s39
	v_add3_u32 v3, v33, v3, s39
	v_lshrrev_b32_e32 v31, 16, v31
	v_and_or_b32 v32, v3, s35, v31
	v_and_b32_sdwa v31, v62, v158 dst_sel:DWORD dst_unused:UNUSED_PAD src0_sel:WORD_1 src1_sel:DWORD
	v_and_b32_sdwa v3, v63, v158 dst_sel:DWORD dst_unused:UNUSED_PAD src0_sel:WORD_1 src1_sel:DWORD
	v_add3_u32 v31, v62, v31, s39
	v_add3_u32 v3, v63, v3, s39
	v_lshrrev_b32_e32 v31, 16, v31
	v_and_b32_sdwa v33, v58, v158 dst_sel:DWORD dst_unused:UNUSED_PAD src0_sel:WORD_1 src1_sel:DWORD
	v_and_or_b32 v31, v3, s35, v31
	v_and_b32_sdwa v3, v59, v158 dst_sel:DWORD dst_unused:UNUSED_PAD src0_sel:WORD_1 src1_sel:DWORD
	v_add3_u32 v33, v58, v33, s39
	v_add3_u32 v3, v59, v3, s39
	v_lshrrev_b32_e32 v33, 16, v33
	v_and_or_b32 v33, v3, s35, v33
	v_permlane32_swap_b32_e32 v30, v32
	s_nop 0
	v_permlane32_swap_b32_e32 v31, v33
	global_store_dwordx4 v[84:85], v[30:33], off offset:2048
	ds_read_b128 v[30:33], v193 offset:64
	s_nop 0
	ds_read_b128 v[58:61], v193 offset:96
	global_load_dwordx4 v[62:65], v[10:11], off offset:64
	s_waitcnt vmcnt(2)
	v_mov_b32_e32 v3, v28
	s_nop 1
	v_permlane32_swap_b32_e32 v26, v3
	v_pk_mul_f32 v[70:71], v[122:123], v[2:3] op_sel_hi:[1,0]
	v_mov_b32_e32 v69, v29
	v_lshlrev_b32_e32 v28, 16, v26
	v_and_b32_e32 v29, 0xffff0000, v26
	v_permlane32_swap_b32_e32 v27, v69
	v_lshlrev_b32_e32 v26, 16, v27
	v_and_b32_e32 v27, 0xffff0000, v27
	v_lshlrev_b32_e32 v66, 16, v3
	v_and_b32_e32 v67, 0xffff0000, v3
	v_lshlrev_b32_e32 v68, 16, v69
	v_and_b32_e32 v69, 0xffff0000, v69
	s_waitcnt lgkmcnt(1)
	v_pk_mul_f32 v[30:31], v[30:31], v[70:71]
	s_nop 0
	v_pk_mul_f32 v[28:29], v[30:31], v[28:29]
	v_pk_mul_f32 v[30:31], v[118:119], v[2:3] op_sel_hi:[1,0]
	s_nop 0
	v_pk_mul_f32 v[30:31], v[32:33], v[30:31]
	s_nop 0
	v_pk_mul_f32 v[30:31], v[30:31], v[26:27]
	v_pk_mul_f32 v[26:27], v[160:161], v[2:3] op_sel_hi:[1,0]
	s_waitcnt lgkmcnt(0)
	v_pk_mul_f32 v[26:27], v[58:59], v[26:27]
	s_nop 0
	v_pk_mul_f32 v[32:33], v[26:27], v[66:67]
	v_pk_mul_f32 v[26:27], v[120:121], v[2:3] op_sel_hi:[1,0]
	v_and_b32_sdwa v3, v29, v158 dst_sel:DWORD dst_unused:UNUSED_PAD src0_sel:WORD_1 src1_sel:DWORD
	v_pk_mul_f32 v[26:27], v[60:61], v[26:27]
	v_add3_u32 v3, v29, v3, s39
	v_pk_mul_f32 v[58:59], v[26:27], v[68:69]
	v_and_b32_sdwa v26, v28, v158 dst_sel:DWORD dst_unused:UNUSED_PAD src0_sel:WORD_1 src1_sel:DWORD
	v_add3_u32 v26, v28, v26, s39
	v_lshrrev_b32_e32 v26, 16, v26
	v_and_b32_sdwa v27, v32, v158 dst_sel:DWORD dst_unused:UNUSED_PAD src0_sel:WORD_1 src1_sel:DWORD
	v_and_or_b32 v26, v3, s35, v26
	v_and_b32_sdwa v3, v33, v158 dst_sel:DWORD dst_unused:UNUSED_PAD src0_sel:WORD_1 src1_sel:DWORD
	v_add3_u32 v27, v32, v27, s39
	v_add3_u32 v3, v33, v3, s39
	v_lshrrev_b32_e32 v27, 16, v27
	v_and_or_b32 v28, v3, s35, v27
	v_and_b32_sdwa v27, v30, v158 dst_sel:DWORD dst_unused:UNUSED_PAD src0_sel:WORD_1 src1_sel:DWORD
	v_and_b32_sdwa v3, v31, v158 dst_sel:DWORD dst_unused:UNUSED_PAD src0_sel:WORD_1 src1_sel:DWORD
	v_add3_u32 v27, v30, v27, s39
	v_add3_u32 v3, v31, v3, s39
	v_lshrrev_b32_e32 v27, 16, v27
	v_and_b32_sdwa v29, v58, v158 dst_sel:DWORD dst_unused:UNUSED_PAD src0_sel:WORD_1 src1_sel:DWORD
	v_and_or_b32 v27, v3, s35, v27
	v_and_b32_sdwa v3, v59, v158 dst_sel:DWORD dst_unused:UNUSED_PAD src0_sel:WORD_1 src1_sel:DWORD
	v_add3_u32 v29, v58, v29, s39
	v_add3_u32 v3, v59, v3, s39
	v_lshrrev_b32_e32 v29, 16, v29
	v_and_or_b32 v29, v3, s35, v29
	v_permlane32_swap_b32_e32 v26, v28
	s_nop 0
	v_permlane32_swap_b32_e32 v27, v29
	global_store_dwordx4 v[10:11], v[26:29], off offset:32
	ds_read_b128 v[26:29], v193 offset:128
	s_nop 0
	ds_read_b128 v[30:33], v193 offset:160
	s_waitcnt vmcnt(1)
	v_mov_b32_e32 v3, v64
	s_nop 1
	v_permlane32_swap_b32_e32 v62, v3
	v_mov_b32_e32 v58, v65
	s_nop 1
	v_permlane32_swap_b32_e32 v63, v58
	v_pk_mul_f32 v[50:51], v[50:51], v[2:3] op_sel_hi:[1,0]
	v_lshlrev_b32_e32 v64, 16, v62
	v_and_b32_e32 v65, 0xffff0000, v62
	v_lshlrev_b32_e32 v62, 16, v63
	v_and_b32_e32 v63, 0xffff0000, v63
	v_pk_mul_f32 v[54:55], v[54:55], v[2:3] op_sel_hi:[1,0]
	v_lshlrev_b32_e32 v66, 16, v3
	v_and_b32_e32 v67, 0xffff0000, v3
	v_lshlrev_b32_e32 v68, 16, v58
	v_and_b32_e32 v69, 0xffff0000, v58
	global_load_dwordx4 v[58:61], v[10:11], off offset:96
	s_waitcnt lgkmcnt(1)
	v_pk_mul_f32 v[28:29], v[50:51], v[28:29]
	v_pk_mul_f32 v[26:27], v[54:55], v[26:27]
	v_pk_mul_f32 v[50:51], v[28:29], v[62:63]
	v_pk_mul_f32 v[28:29], v[56:57], v[2:3] op_sel_hi:[1,0]
	v_pk_mul_f32 v[26:27], v[26:27], v[64:65]
	s_waitcnt lgkmcnt(0)
	v_pk_mul_f32 v[28:29], v[28:29], v[30:31]
	v_pk_mul_f32 v[30:31], v[52:53], v[2:3] op_sel_hi:[1,0]
	v_pk_mul_f32 v[28:29], v[28:29], v[66:67]
	v_pk_mul_f32 v[30:31], v[30:31], v[32:33]
	v_and_b32_sdwa v32, v26, v158 dst_sel:DWORD dst_unused:UNUSED_PAD src0_sel:WORD_1 src1_sel:DWORD
	v_and_b32_sdwa v3, v27, v158 dst_sel:DWORD dst_unused:UNUSED_PAD src0_sel:WORD_1 src1_sel:DWORD
	v_add3_u32 v26, v26, v32, s39
	v_add3_u32 v3, v27, v3, s39
	v_lshrrev_b32_e32 v26, 16, v26
	v_and_b32_sdwa v27, v28, v158 dst_sel:DWORD dst_unused:UNUSED_PAD src0_sel:WORD_1 src1_sel:DWORD
	v_and_or_b32 v26, v3, s35, v26
	v_and_b32_sdwa v3, v29, v158 dst_sel:DWORD dst_unused:UNUSED_PAD src0_sel:WORD_1 src1_sel:DWORD
	v_add3_u32 v27, v28, v27, s39
	v_add3_u32 v3, v29, v3, s39
	v_lshrrev_b32_e32 v27, 16, v27
	v_and_or_b32 v28, v3, s35, v27
	v_and_b32_sdwa v27, v50, v158 dst_sel:DWORD dst_unused:UNUSED_PAD src0_sel:WORD_1 src1_sel:DWORD
	v_pk_mul_f32 v[30:31], v[30:31], v[68:69]
	v_and_b32_sdwa v3, v51, v158 dst_sel:DWORD dst_unused:UNUSED_PAD src0_sel:WORD_1 src1_sel:DWORD
	v_add3_u32 v27, v50, v27, s39
	v_add3_u32 v3, v51, v3, s39
	v_lshrrev_b32_e32 v27, 16, v27
	v_and_b32_sdwa v29, v30, v158 dst_sel:DWORD dst_unused:UNUSED_PAD src0_sel:WORD_1 src1_sel:DWORD
	v_and_or_b32 v27, v3, s35, v27
	v_and_b32_sdwa v3, v31, v158 dst_sel:DWORD dst_unused:UNUSED_PAD src0_sel:WORD_1 src1_sel:DWORD
	v_add3_u32 v29, v30, v29, s39
	v_add3_u32 v3, v31, v3, s39
	v_lshrrev_b32_e32 v29, 16, v29
	v_and_or_b32 v29, v3, s35, v29
	v_permlane32_swap_b32_e32 v26, v28
	s_nop 0
	v_permlane32_swap_b32_e32 v27, v29
	global_store_dwordx4 v[10:11], v[26:29], off offset:64
	ds_read_b128 v[26:29], v193 offset:192
	s_nop 0
	ds_read_b128 v[30:33], v193 offset:224
	global_load_dwordx4 v[50:53], v[10:11], off offset:128
	s_waitcnt vmcnt(2)
	v_mov_b32_e32 v3, v60
	s_nop 1
	v_permlane32_swap_b32_e32 v58, v3
	v_pk_mul_f32 v[42:43], v[42:43], v[2:3] op_sel_hi:[1,0]
	v_permlane32_swap_b32_e32 v59, v61
	v_lshlrev_b32_e32 v56, 16, v59
	v_and_b32_e32 v57, 0xffff0000, v59
	v_lshlrev_b32_e32 v54, 16, v58
	v_and_b32_e32 v55, 0xffff0000, v58
	v_lshlrev_b32_e32 v58, 16, v3
	v_and_b32_e32 v59, 0xffff0000, v3
	v_lshlrev_b32_e32 v60, 16, v61
	v_and_b32_e32 v61, 0xffff0000, v61
	s_waitcnt lgkmcnt(1)
	v_pk_mul_f32 v[26:27], v[42:43], v[26:27]
	v_pk_mul_f32 v[42:43], v[44:45], v[2:3] op_sel_hi:[1,0]
	v_pk_mul_f32 v[26:27], v[26:27], v[54:55]
	v_pk_mul_f32 v[28:29], v[42:43], v[28:29]
	s_nop 0
	v_pk_mul_f32 v[42:43], v[28:29], v[56:57]
	v_pk_mul_f32 v[28:29], v[46:47], v[2:3] op_sel_hi:[1,0]
	s_waitcnt lgkmcnt(0)
	v_pk_mul_f32 v[28:29], v[28:29], v[30:31]
	v_pk_mul_f32 v[30:31], v[48:49], v[2:3] op_sel_hi:[1,0]
	v_pk_mul_f32 v[28:29], v[28:29], v[58:59]
	v_pk_mul_f32 v[30:31], v[30:31], v[32:33]
	v_and_b32_sdwa v32, v26, v158 dst_sel:DWORD dst_unused:UNUSED_PAD src0_sel:WORD_1 src1_sel:DWORD
	v_and_b32_sdwa v3, v27, v158 dst_sel:DWORD dst_unused:UNUSED_PAD src0_sel:WORD_1 src1_sel:DWORD
	v_add3_u32 v26, v26, v32, s39
	v_add3_u32 v3, v27, v3, s39
	v_lshrrev_b32_e32 v26, 16, v26
	v_and_b32_sdwa v27, v28, v158 dst_sel:DWORD dst_unused:UNUSED_PAD src0_sel:WORD_1 src1_sel:DWORD
	v_and_or_b32 v26, v3, s35, v26
	v_and_b32_sdwa v3, v29, v158 dst_sel:DWORD dst_unused:UNUSED_PAD src0_sel:WORD_1 src1_sel:DWORD
	v_add3_u32 v27, v28, v27, s39
	v_add3_u32 v3, v29, v3, s39
	v_lshrrev_b32_e32 v27, 16, v27
	v_and_or_b32 v28, v3, s35, v27
	v_and_b32_sdwa v27, v42, v158 dst_sel:DWORD dst_unused:UNUSED_PAD src0_sel:WORD_1 src1_sel:DWORD
	v_pk_mul_f32 v[30:31], v[30:31], v[60:61]
	v_and_b32_sdwa v3, v43, v158 dst_sel:DWORD dst_unused:UNUSED_PAD src0_sel:WORD_1 src1_sel:DWORD
	v_add3_u32 v27, v42, v27, s39
	v_add3_u32 v3, v43, v3, s39
	v_lshrrev_b32_e32 v27, 16, v27
	v_and_b32_sdwa v29, v30, v158 dst_sel:DWORD dst_unused:UNUSED_PAD src0_sel:WORD_1 src1_sel:DWORD
	v_and_or_b32 v27, v3, s35, v27
	v_and_b32_sdwa v3, v31, v158 dst_sel:DWORD dst_unused:UNUSED_PAD src0_sel:WORD_1 src1_sel:DWORD
	v_add3_u32 v29, v30, v29, s39
	v_add3_u32 v3, v31, v3, s39
	v_lshrrev_b32_e32 v29, 16, v29
	v_and_or_b32 v29, v3, s35, v29
	v_permlane32_swap_b32_e32 v26, v28
	s_nop 0
	v_permlane32_swap_b32_e32 v27, v29
	global_store_dwordx4 v[10:11], v[26:29], off offset:96
	ds_read_b128 v[26:29], v193 offset:256
	s_nop 0
	ds_read_b128 v[30:33], v193 offset:288
	s_waitcnt vmcnt(1)
	v_mov_b32_e32 v3, v52
	s_nop 1
	v_permlane32_swap_b32_e32 v50, v3
	v_mov_b32_e32 v42, v53
	s_nop 1
	v_permlane32_swap_b32_e32 v51, v42
	v_pk_mul_f32 v[34:35], v[34:35], v[2:3] op_sel_hi:[1,0]
	v_lshlrev_b32_e32 v48, 16, v51
	v_and_b32_e32 v49, 0xffff0000, v51
	v_pk_mul_f32 v[38:39], v[38:39], v[2:3] op_sel_hi:[1,0]
	v_lshlrev_b32_e32 v46, 16, v50
	v_and_b32_e32 v47, 0xffff0000, v50
	v_lshlrev_b32_e32 v50, 16, v3
	v_and_b32_e32 v51, 0xffff0000, v3
	v_lshlrev_b32_e32 v52, 16, v42
	v_and_b32_e32 v53, 0xffff0000, v42
	global_load_dwordx4 v[42:45], v[10:11], off offset:160
	s_waitcnt lgkmcnt(1)
	v_pk_mul_f32 v[28:29], v[34:35], v[28:29]
	v_pk_mul_f32 v[26:27], v[38:39], v[26:27]
	v_pk_mul_f32 v[34:35], v[28:29], v[48:49]
	v_pk_mul_f32 v[28:29], v[40:41], v[2:3] op_sel_hi:[1,0]
	v_pk_mul_f32 v[26:27], v[26:27], v[46:47]
	s_waitcnt lgkmcnt(0)
	v_pk_mul_f32 v[28:29], v[28:29], v[30:31]
	v_pk_mul_f32 v[30:31], v[36:37], v[2:3] op_sel_hi:[1,0]
	v_pk_mul_f32 v[28:29], v[28:29], v[50:51]
	v_pk_mul_f32 v[30:31], v[30:31], v[32:33]
	v_and_b32_sdwa v32, v26, v158 dst_sel:DWORD dst_unused:UNUSED_PAD src0_sel:WORD_1 src1_sel:DWORD
	v_and_b32_sdwa v3, v27, v158 dst_sel:DWORD dst_unused:UNUSED_PAD src0_sel:WORD_1 src1_sel:DWORD
	v_add3_u32 v26, v26, v32, s39
	v_add3_u32 v3, v27, v3, s39
	v_lshrrev_b32_e32 v26, 16, v26
	v_and_b32_sdwa v27, v28, v158 dst_sel:DWORD dst_unused:UNUSED_PAD src0_sel:WORD_1 src1_sel:DWORD
	v_and_or_b32 v26, v3, s35, v26
	v_and_b32_sdwa v3, v29, v158 dst_sel:DWORD dst_unused:UNUSED_PAD src0_sel:WORD_1 src1_sel:DWORD
	v_add3_u32 v27, v28, v27, s39
	v_add3_u32 v3, v29, v3, s39
	v_lshrrev_b32_e32 v27, 16, v27
	v_and_or_b32 v28, v3, s35, v27
	v_and_b32_sdwa v27, v34, v158 dst_sel:DWORD dst_unused:UNUSED_PAD src0_sel:WORD_1 src1_sel:DWORD
	v_pk_mul_f32 v[30:31], v[30:31], v[52:53]
	v_and_b32_sdwa v3, v35, v158 dst_sel:DWORD dst_unused:UNUSED_PAD src0_sel:WORD_1 src1_sel:DWORD
	v_add3_u32 v27, v34, v27, s39
	v_add3_u32 v3, v35, v3, s39
	v_lshrrev_b32_e32 v27, 16, v27
	v_and_b32_sdwa v29, v30, v158 dst_sel:DWORD dst_unused:UNUSED_PAD src0_sel:WORD_1 src1_sel:DWORD
	v_and_or_b32 v27, v3, s35, v27
	v_and_b32_sdwa v3, v31, v158 dst_sel:DWORD dst_unused:UNUSED_PAD src0_sel:WORD_1 src1_sel:DWORD
	v_add3_u32 v29, v30, v29, s39
	v_add3_u32 v3, v31, v3, s39
	v_lshrrev_b32_e32 v29, 16, v29
	v_and_or_b32 v29, v3, s35, v29
	v_permlane32_swap_b32_e32 v26, v28
	s_nop 0
	v_permlane32_swap_b32_e32 v27, v29
	global_store_dwordx4 v[10:11], v[26:29], off offset:128
	ds_read_b128 v[26:29], v193 offset:320
	s_nop 0
	ds_read_b128 v[30:33], v193 offset:352
	global_load_dwordx4 v[34:37], v[10:11], off offset:192
	s_waitcnt vmcnt(2)
	v_mov_b32_e32 v3, v44
	s_nop 1
	v_permlane32_swap_b32_e32 v42, v3
	v_permlane32_swap_b32_e32 v43, v45
	v_pk_mul_f32 v[18:19], v[18:19], v[2:3] op_sel_hi:[1,0]
	v_lshlrev_b32_e32 v40, 16, v43
	v_and_b32_e32 v41, 0xffff0000, v43
	v_pk_mul_f32 v[24:25], v[24:25], v[2:3] op_sel_hi:[1,0]
	v_lshlrev_b32_e32 v38, 16, v42
	v_and_b32_e32 v39, 0xffff0000, v42
	v_lshlrev_b32_e32 v42, 16, v3
	v_and_b32_e32 v43, 0xffff0000, v3
	v_lshlrev_b32_e32 v44, 16, v45
	v_and_b32_e32 v45, 0xffff0000, v45
	s_waitcnt lgkmcnt(1)
	v_pk_mul_f32 v[18:19], v[18:19], v[28:29]
	v_pk_mul_f32 v[24:25], v[24:25], v[26:27]
	v_pk_mul_f32 v[26:27], v[18:19], v[40:41]
	v_pk_mul_f32 v[18:19], v[22:23], v[2:3] op_sel_hi:[1,0]
	v_pk_mul_f32 v[24:25], v[24:25], v[38:39]
	s_waitcnt lgkmcnt(0)
	v_pk_mul_f32 v[18:19], v[18:19], v[30:31]
	s_nop 0
	v_pk_mul_f32 v[22:23], v[18:19], v[42:43]
	v_pk_mul_f32 v[18:19], v[20:21], v[2:3] op_sel_hi:[1,0]
	v_and_b32_sdwa v3, v25, v158 dst_sel:DWORD dst_unused:UNUSED_PAD src0_sel:WORD_1 src1_sel:DWORD
	v_pk_mul_f32 v[18:19], v[18:19], v[32:33]
	v_add3_u32 v3, v25, v3, s39
	v_pk_mul_f32 v[28:29], v[18:19], v[44:45]
	v_and_b32_sdwa v18, v24, v158 dst_sel:DWORD dst_unused:UNUSED_PAD src0_sel:WORD_1 src1_sel:DWORD
	v_add3_u32 v18, v24, v18, s39
	v_lshrrev_b32_e32 v18, 16, v18
	v_and_b32_sdwa v19, v22, v158 dst_sel:DWORD dst_unused:UNUSED_PAD src0_sel:WORD_1 src1_sel:DWORD
	v_and_or_b32 v18, v3, s35, v18
	v_and_b32_sdwa v3, v23, v158 dst_sel:DWORD dst_unused:UNUSED_PAD src0_sel:WORD_1 src1_sel:DWORD
	v_add3_u32 v19, v22, v19, s39
	v_add3_u32 v3, v23, v3, s39
	v_lshrrev_b32_e32 v19, 16, v19
	v_and_or_b32 v20, v3, s35, v19
	v_and_b32_sdwa v19, v26, v158 dst_sel:DWORD dst_unused:UNUSED_PAD src0_sel:WORD_1 src1_sel:DWORD
	v_and_b32_sdwa v3, v27, v158 dst_sel:DWORD dst_unused:UNUSED_PAD src0_sel:WORD_1 src1_sel:DWORD
	v_add3_u32 v19, v26, v19, s39
	v_add3_u32 v3, v27, v3, s39
	v_lshrrev_b32_e32 v19, 16, v19
	v_and_b32_sdwa v21, v28, v158 dst_sel:DWORD dst_unused:UNUSED_PAD src0_sel:WORD_1 src1_sel:DWORD
	v_and_or_b32 v19, v3, s35, v19
	v_and_b32_sdwa v3, v29, v158 dst_sel:DWORD dst_unused:UNUSED_PAD src0_sel:WORD_1 src1_sel:DWORD
	v_add3_u32 v21, v28, v21, s39
	v_add3_u32 v3, v29, v3, s39
	v_lshrrev_b32_e32 v21, 16, v21
	v_and_or_b32 v21, v3, s35, v21
	v_permlane32_swap_b32_e32 v18, v20
	s_nop 0
	v_permlane32_swap_b32_e32 v19, v21
	global_store_dwordx4 v[10:11], v[18:21], off offset:160
	ds_read_b128 v[18:21], v193 offset:384
	s_nop 0
	ds_read_b128 v[22:25], v193 offset:416
	v_pk_mul_f32 v[8:9], v[8:9], v[2:3] op_sel_hi:[1,0]
	v_pk_mul_f32 v[16:17], v[16:17], v[2:3] op_sel_hi:[1,0]
	v_pk_mul_f32 v[6:7], v[6:7], v[2:3] op_sel_hi:[1,0]
	v_pk_mul_f32 v[4:5], v[4:5], v[2:3] op_sel_hi:[1,0]
	s_waitcnt vmcnt(1)
	v_mov_b32_e32 v3, v36
	v_mov_b32_e32 v33, v37
	s_nop 0
	v_permlane32_swap_b32_e32 v34, v3
	v_permlane32_swap_b32_e32 v35, v33
	v_lshlrev_b32_e32 v26, 16, v34
	v_and_b32_e32 v27, 0xffff0000, v34
	v_lshlrev_b32_e32 v32, 16, v33
	v_and_b32_e32 v33, 0xffff0000, v33
	v_lshlrev_b32_e32 v30, 16, v3
	v_and_b32_e32 v31, 0xffff0000, v3
	v_lshlrev_b32_e32 v28, 16, v35
	v_and_b32_e32 v29, 0xffff0000, v35
	s_waitcnt lgkmcnt(1)
	v_pk_mul_f32 v[8:9], v[8:9], v[18:19]
	s_waitcnt lgkmcnt(0)
	v_pk_mul_f32 v[4:5], v[4:5], v[24:25]
	v_pk_mul_f32 v[8:9], v[8:9], v[26:27]
	v_pk_mul_f32 v[18:19], v[4:5], v[32:33]
	v_and_b32_sdwa v4, v8, v158 dst_sel:DWORD dst_unused:UNUSED_PAD src0_sel:WORD_1 src1_sel:DWORD
	v_pk_mul_f32 v[6:7], v[6:7], v[22:23]
	v_and_b32_sdwa v3, v9, v158 dst_sel:DWORD dst_unused:UNUSED_PAD src0_sel:WORD_1 src1_sel:DWORD
	v_add3_u32 v4, v8, v4, s39
	v_pk_mul_f32 v[6:7], v[6:7], v[30:31]
	v_add3_u32 v3, v9, v3, s39
	v_lshrrev_b32_e32 v4, 16, v4
	v_and_or_b32 v4, v3, s35, v4
	v_and_b32_sdwa v3, v6, v158 dst_sel:DWORD dst_unused:UNUSED_PAD src0_sel:WORD_1 src1_sel:DWORD
	v_pk_mul_f32 v[16:17], v[16:17], v[20:21]
	v_and_b32_sdwa v5, v7, v158 dst_sel:DWORD dst_unused:UNUSED_PAD src0_sel:WORD_1 src1_sel:DWORD
	v_add3_u32 v3, v6, v3, s39
	v_pk_mul_f32 v[16:17], v[16:17], v[28:29]
	v_add3_u32 v5, v7, v5, s39
	v_lshrrev_b32_e32 v3, 16, v3
	v_and_or_b32 v6, v5, s35, v3
	v_and_b32_sdwa v5, v16, v158 dst_sel:DWORD dst_unused:UNUSED_PAD src0_sel:WORD_1 src1_sel:DWORD
	v_and_b32_sdwa v3, v17, v158 dst_sel:DWORD dst_unused:UNUSED_PAD src0_sel:WORD_1 src1_sel:DWORD
	v_add3_u32 v5, v16, v5, s39
	v_add3_u32 v3, v17, v3, s39
	v_lshrrev_b32_e32 v5, 16, v5
	v_and_b32_sdwa v7, v18, v158 dst_sel:DWORD dst_unused:UNUSED_PAD src0_sel:WORD_1 src1_sel:DWORD
	v_and_or_b32 v5, v3, s35, v5
	v_and_b32_sdwa v3, v19, v158 dst_sel:DWORD dst_unused:UNUSED_PAD src0_sel:WORD_1 src1_sel:DWORD
	v_add3_u32 v7, v18, v7, s39
	v_add3_u32 v3, v19, v3, s39
	v_lshrrev_b32_e32 v7, 16, v7
	v_and_or_b32 v7, v3, s35, v7
	v_permlane32_swap_b32_e32 v4, v6
	s_nop 0
	v_permlane32_swap_b32_e32 v5, v7
	global_store_dwordx4 v[10:11], v[4:7], off offset:192
	ds_read_b128 v[4:7], v193 offset:448
	s_nop 0
	ds_read_b128 v[16:19], v193 offset:480
	v_mov_b32_e32 v8, v144
	v_mov_b32_e32 v9, v14
	v_mov_b32_e32 v20, v108
	v_mov_b32_e32 v21, v12
	v_mov_b32_e32 v14, v145
	v_mov_b32_e32 v12, v109
	v_mov_b32_e32 v25, v80
	v_mov_b32_e32 v27, v81
	v_pk_mul_f32 v[8:9], v[8:9], v[2:3] op_sel_hi:[1,0]
	v_pk_mul_f32 v[20:21], v[20:21], v[2:3] op_sel_hi:[1,0]
	v_pk_mul_f32 v[14:15], v[14:15], v[2:3] op_sel_hi:[1,0]
	v_pk_mul_f32 v[2:3], v[12:13], v[2:3] op_sel_hi:[1,0]
	v_permlane32_swap_b32_e32 v78, v25
	v_permlane32_swap_b32_e32 v79, v27
	v_lshlrev_b32_e32 v12, 16, v78
	v_and_b32_e32 v13, 0xffff0000, v78
	v_lshlrev_b32_e32 v22, 16, v79
	v_and_b32_e32 v23, 0xffff0000, v79
	v_lshlrev_b32_e32 v24, 16, v25
	v_and_b32_e32 v25, 0xffff0000, v25
	v_lshlrev_b32_e32 v26, 16, v27
	v_and_b32_e32 v27, 0xffff0000, v27
	s_waitcnt lgkmcnt(1)
	v_pk_mul_f32 v[4:5], v[8:9], v[4:5]
	s_waitcnt lgkmcnt(0)
	v_pk_mul_f32 v[8:9], v[20:21], v[16:17]
	v_pk_mul_f32 v[6:7], v[14:15], v[6:7]
	v_pk_mul_f32 v[2:3], v[2:3], v[18:19]
	v_pk_mul_f32 v[4:5], v[4:5], v[12:13]
	v_pk_mul_f32 v[8:9], v[8:9], v[24:25]
	v_pk_mul_f32 v[6:7], v[6:7], v[22:23]
	v_pk_mul_f32 v[2:3], v[2:3], v[26:27]
	v_and_b32_sdwa v13, v4, v158 dst_sel:DWORD dst_unused:UNUSED_PAD src0_sel:WORD_1 src1_sel:DWORD
	v_and_b32_sdwa v15, v8, v158 dst_sel:DWORD dst_unused:UNUSED_PAD src0_sel:WORD_1 src1_sel:DWORD
	v_and_b32_sdwa v17, v6, v158 dst_sel:DWORD dst_unused:UNUSED_PAD src0_sel:WORD_1 src1_sel:DWORD
	v_and_b32_sdwa v19, v2, v158 dst_sel:DWORD dst_unused:UNUSED_PAD src0_sel:WORD_1 src1_sel:DWORD
	v_and_b32_sdwa v12, v5, v158 dst_sel:DWORD dst_unused:UNUSED_PAD src0_sel:WORD_1 src1_sel:DWORD
	v_and_b32_sdwa v14, v9, v158 dst_sel:DWORD dst_unused:UNUSED_PAD src0_sel:WORD_1 src1_sel:DWORD
	v_and_b32_sdwa v16, v7, v158 dst_sel:DWORD dst_unused:UNUSED_PAD src0_sel:WORD_1 src1_sel:DWORD
	v_and_b32_sdwa v18, v3, v158 dst_sel:DWORD dst_unused:UNUSED_PAD src0_sel:WORD_1 src1_sel:DWORD
	v_add3_u32 v4, v4, v13, s39
	v_add3_u32 v8, v8, v15, s39
	v_add3_u32 v6, v6, v17, s39
	v_add3_u32 v2, v2, v19, s39
	v_add3_u32 v5, v5, v12, s39
	v_add3_u32 v9, v9, v14, s39
	v_add3_u32 v7, v7, v16, s39
	v_add3_u32 v12, v3, v18, s39
	v_lshrrev_b32_e32 v3, 16, v4
	v_lshrrev_b32_e32 v4, 16, v8
	v_lshrrev_b32_e32 v6, 16, v6
	v_lshrrev_b32_e32 v8, 16, v2
	v_and_or_b32 v2, v5, s35, v3
	v_and_or_b32 v4, v9, s35, v4
	v_and_or_b32 v3, v7, s35, v6
	v_and_or_b32 v5, v12, s35, v8
	v_permlane32_swap_b32_e32 v2, v4
	s_nop 0
	v_permlane32_swap_b32_e32 v3, v5
	global_store_dwordx4 v[10:11], v[2:5], off offset:224
	s_branch .LBB0_972
